# diff-attention: process the long query block (63-ci) before the short one so CUs of an XCD stream K/V tiles in step (L2 locality)
# speedup vs baseline: 1.0038x; 1.0038x over previous
.LBB0_785:
	s_lshr_b32 s52, s51, 1
	s_lshl_b32 s2, s52, 7
	v_readlane_b32 s3, v251, 38
	s_add_i32 s4, s3, s2
	s_lshl_b64 s[34:35], s[4:5], 1
	s_bitcmp0_b32 s51, 0
	v_readlane_b32 s2, v251, 34
	v_readlane_b32 s3, v251, 36
	s_cselect_b32 s3, s3, s2
	v_readlane_b32 s60, v251, 32
	v_readlane_b32 s61, v251, 33
	s_or_b32 s2, s60, s3
	s_mul_i32 s30, s61, 0x3000
	s_mul_hi_u32 s4, s2, 0x3000
	v_writelane_b32 v251, s30, 44
	s_add_i32 s4, s4, s30
	s_mul_i32 s30, s2, 0x3000
	s_add_u32 s30, s48, s30
	s_addc_u32 s4, s49, s4
	s_add_u32 s38, s30, s34
	s_addc_u32 s39, s4, s35
	s_add_u32 s36, s40, s34
	v_readfirstlane_b32 s4, v208
	s_addc_u32 s37, s41, s35
	s_ashr_i32 s56, s4, 6
	s_and_b32 s4, s4, 0x3fffffc0
	s_lshl_b32 s4, s4, 2
	s_lshl_b32 s31, s56, 3
	s_lshl_b32 s30, s56, 5
	s_add_i32 s4, s4, 0
	v_or_b32_e32 v0, s31, v212
	v_bitop3_b32 v7, s31, v229, v214 bitop3:0xc8
	s_lshl_b32 s31, s56, 2
	s_add_i32 s57, s4, 0x18000
	s_add_i32 s4, s30, s3
	s_and_b32 s58, s31, 4
	s_lshl_b32 s53, s56, 11
	s_lshl_b32 s54, s56, 12
	s_ashr_i32 s31, s30, 31
	s_mul_i32 s55, s56, 0x60000
	s_mul_hi_i32 s59, s30, 0x3000
	s_add_u32 s38, s38, s55
	v_or3_b32 v2, v215, v7, s58
	s_addc_u32 s39, s39, s59
	s_lshr_b32 s3, s3, 6
	v_mul_lo_u32 v2, v2, s45
	s_or_b32 s55, s3, 3
	v_or_b32_e32 v8, v2, v216
	v_lshl_add_u64 v[2:3], s[38:39], 0, v[194:195]
	s_mov_b64 s[38:39], 0x1800
	s_cmp_lg_u32 0, -1
	v_lshl_add_u64 v[4:5], v[2:3], 0, s[38:39]
	s_movk_i32 s38, 0x1000
	s_cselect_b32 s3, 0, 0
	v_mul_lo_u32 v0, v0, s44
	v_add_co_u32_e32 v2, vcc, s38, v2
	s_add_i32 s38, s3, s53
	v_or_b32_e32 v6, v0, v213
	v_or_b32_e32 v0, v0, v228
	v_addc_co_u32_e32 v3, vcc, 0, v3, vcc
	global_load_dwordx4 v[162:165], v[4:5], off offset:32
	global_load_dwordx4 v[166:169], v[4:5], off offset:64
	global_load_dwordx4 v[170:173], v[4:5], off offset:96
	global_load_dwordx4 v[174:177], v[4:5], off offset:128
	global_load_dwordx4 v[178:181], v[4:5], off offset:160
	global_load_dwordx4 v[182:185], v[4:5], off offset:192
	global_load_dwordx4 v[186:189], v[2:3], off offset:2048
	global_load_dwordx4 v[190:193], v[4:5], off offset:224
	s_add_i32 m0, s38, 0x10000
	v_add_u32_e32 v0, 0xc000, v0
	global_load_lds_dwordx4 v6, s[36:37]
	s_add_i32 m0, s38, 0x10400
	s_add_i32 s3, s54, s3
	global_load_lds_dwordx4 v0, s[36:37]
	v_lshlrev_b32_e32 v0, 1, v8
	v_lshl_add_u64 v[2:3], s[8:9], 0, v[0:1]
	s_mov_b32 m0, s3
	s_mov_b64 s[36:37], 0x80
	global_load_lds_dwordx4 v0, s[8:9]
	v_lshl_add_u64 v[4:5], v[2:3], 0, s[36:37]
	s_add_i32 m0, s3, 0x400
	s_mov_b64 s[36:37], 0x100
	global_load_lds_dwordx4 v[4:5], off
	v_lshl_add_u64 v[4:5], v[2:3], 0, s[36:37]
	s_add_i32 m0, s3, 0x800
	s_mov_b64 s[36:37], 0x180
	global_load_lds_dwordx4 v[4:5], off
	v_lshl_add_u64 v[2:3], v[2:3], 0, s[36:37]
	s_add_i32 m0, s3, 0xc00
	v_add3_u32 v0, v215, v7, s58
	global_load_lds_dwordx4 v[2:3], off
	v_mul_lo_u32 v0, v0, s45
	v_or_b32_e32 v0, v216, v0
	v_readlane_b32 s36, v251, 40
	v_lshlrev_b32_e32 v0, 1, v0
	v_readlane_b32 s37, v251, 41
	s_mul_i32 s56, s56, 0x18000
	v_mov_b32_e32 v14, v1
	v_lshl_add_u64 v[196:197], s[36:37], 0, v[0:1]
	v_add3_u32 v0, v226, s56, v228
	v_lshl_add_u64 v[198:199], s[34:35], 0, v[0:1]
	v_add_u32_e32 v0, s56, v227
	v_mov_b32_e32 v15, v1
	s_waitcnt vmcnt(0)
	v_lshl_add_u64 v[200:201], s[34:35], 0, v[0:1]
	v_mov_b32_e32 v0, v1
	v_mov_b32_e32 v2, v1
	v_mov_b32_e32 v3, v1
	v_mov_b32_e32 v4, v1
	v_mov_b32_e32 v5, v1
	v_mov_b32_e32 v6, v1
	v_mov_b32_e32 v7, v1
	v_mov_b32_e32 v8, v1
	v_mov_b32_e32 v9, v1
	v_mov_b32_e32 v10, v1
	v_mov_b32_e32 v11, v1
	v_mov_b32_e32 v12, v1
	v_mov_b32_e32 v13, v1
	s_waitcnt vmcnt(0)
	v_mov_b64_e32 v[128:129], v[14:15]
	v_mov_b64_e32 v[112:113], v[14:15]
	v_mov_b64_e32 v[96:97], v[14:15]
	v_mov_b64_e32 v[80:81], v[14:15]
	v_mov_b64_e32 v[64:65], v[14:15]
	v_mov_b64_e32 v[48:49], v[14:15]
	v_mov_b64_e32 v[32:33], v[14:15]
	v_mov_b64_e32 v[126:127], v[12:13]
	v_mov_b64_e32 v[124:125], v[10:11]
	v_mov_b64_e32 v[122:123], v[8:9]
	v_mov_b64_e32 v[120:121], v[6:7]
	v_mov_b64_e32 v[118:119], v[4:5]
	v_mov_b64_e32 v[116:117], v[2:3]
	v_mov_b64_e32 v[114:115], v[0:1]
	v_mov_b64_e32 v[110:111], v[12:13]
	v_mov_b64_e32 v[108:109], v[10:11]
	v_mov_b64_e32 v[106:107], v[8:9]
	v_mov_b64_e32 v[104:105], v[6:7]
	v_mov_b64_e32 v[102:103], v[4:5]
	v_mov_b64_e32 v[100:101], v[2:3]
	v_mov_b64_e32 v[98:99], v[0:1]
	v_mov_b64_e32 v[94:95], v[12:13]
	v_mov_b64_e32 v[92:93], v[10:11]
	v_mov_b64_e32 v[90:91], v[8:9]
	v_mov_b64_e32 v[88:89], v[6:7]
	v_mov_b64_e32 v[86:87], v[4:5]
	v_mov_b64_e32 v[84:85], v[2:3]
	v_mov_b64_e32 v[82:83], v[0:1]
	v_mov_b64_e32 v[78:79], v[12:13]
	v_mov_b64_e32 v[76:77], v[10:11]
	v_mov_b64_e32 v[74:75], v[8:9]
	v_mov_b64_e32 v[72:73], v[6:7]
	v_mov_b64_e32 v[70:71], v[4:5]
	v_mov_b64_e32 v[68:69], v[2:3]
	v_mov_b64_e32 v[66:67], v[0:1]
	v_mov_b64_e32 v[62:63], v[12:13]
	v_mov_b64_e32 v[60:61], v[10:11]
	v_mov_b64_e32 v[58:59], v[8:9]
	v_mov_b64_e32 v[56:57], v[6:7]
	v_mov_b64_e32 v[54:55], v[4:5]
	v_mov_b64_e32 v[52:53], v[2:3]
	v_mov_b64_e32 v[50:51], v[0:1]
	v_mov_b64_e32 v[46:47], v[12:13]
	v_mov_b64_e32 v[44:45], v[10:11]
	v_mov_b64_e32 v[42:43], v[8:9]
	v_mov_b64_e32 v[40:41], v[6:7]
	v_mov_b64_e32 v[38:39], v[4:5]
	v_mov_b64_e32 v[36:37], v[2:3]
	v_mov_b64_e32 v[34:35], v[0:1]
	v_mov_b64_e32 v[30:31], v[12:13]
	v_mov_b64_e32 v[28:29], v[10:11]
	v_mov_b64_e32 v[26:27], v[8:9]
	v_mov_b64_e32 v[24:25], v[6:7]
	v_mov_b64_e32 v[22:23], v[4:5]
	v_mov_b64_e32 v[20:21], v[2:3]
	v_mov_b64_e32 v[18:19], v[0:1]
	v_mov_b64_e32 v[16:17], v[14:15]
	s_mov_b32 s3, s61
	v_add_u32_e32 v233, s4, v211
	v_lshl_add_u32 v232, v209, 2, s57
	v_lshl_add_u32 v231, v210, 2, s57
	v_mov_b32_e32 v237, 0xf149f2ca
	s_movk_i32 s56, 0x7f
	s_mov_b64 s[34:35], s[6:7]
	s_mov_b32 s57, 2
	v_mov_b64_e32 v[14:15], v[12:13]
	v_mov_b64_e32 v[12:13], v[10:11]
	v_mov_b64_e32 v[10:11], v[8:9]
	v_mov_b64_e32 v[8:9], v[6:7]
	v_mov_b64_e32 v[6:7], v[4:5]
	v_mov_b64_e32 v[4:5], v[2:3]
	v_mov_b64_e32 v[2:3], v[0:1]
	v_mov_b32_e32 v0, 0
	s_waitcnt lgkmcnt(0)
	s_barrier
	s_branch .LBB0_788

.LBB0_2405:
	s_lshr_b32 s56, s51, 1
	s_lshl_b32 s2, s56, 7
	v_readlane_b32 s3, v251, 38
	s_add_i32 s4, s3, s2
	s_lshl_b64 s[38:39], s[4:5], 1
	s_bitcmp0_b32 s51, 0
	v_readlane_b32 s2, v251, 34
	v_readlane_b32 s3, v251, 36
	s_cselect_b32 s3, s3, s2
	v_readlane_b32 s64, v251, 32
	s_or_b32 s2, s64, s3
	s_mul_hi_u32 s4, s2, 0x3000
	v_readlane_b32 s36, v251, 44
	s_add_i32 s4, s4, s36
	s_mul_i32 s36, s2, 0x3000
	s_add_u32 s36, s48, s36
	s_addc_u32 s4, s49, s4
	s_add_u32 s42, s36, s38
	s_addc_u32 s43, s4, s39
	s_add_u32 s40, s44, s38
	v_readfirstlane_b32 s4, v208
	s_addc_u32 s41, s45, s39
	s_ashr_i32 s60, s4, 6
	s_and_b32 s4, s4, 0x3fffffc0
	s_lshl_b32 s4, s4, 2
	s_lshl_b32 s37, s60, 3
	s_lshl_b32 s36, s60, 5
	s_add_i32 s4, s4, 0
	v_or_b32_e32 v0, s37, v212
	v_bitop3_b32 v7, s37, v229, v214 bitop3:0xc8
	s_lshl_b32 s37, s60, 2
	s_add_i32 s61, s4, 0x18000
	s_add_i32 s4, s36, s3
	s_and_b32 s62, s37, 4
	s_lshl_b32 s57, s60, 11
	s_lshl_b32 s58, s60, 12
	s_ashr_i32 s37, s36, 31
	s_mul_i32 s59, s60, 0x60000
	s_mul_hi_i32 s63, s36, 0x3000
	s_add_u32 s42, s42, s59
	v_or3_b32 v2, v215, v7, s62
	s_addc_u32 s43, s43, s63
	s_lshr_b32 s3, s3, 6
	v_mul_lo_u32 v2, v2, s52
	s_or_b32 s59, s3, 3
	v_or_b32_e32 v8, v2, v216
	v_lshl_add_u64 v[2:3], s[42:43], 0, v[194:195]
	s_mov_b64 s[42:43], 0x1800
	s_cmp_lg_u32 0, -1
	v_lshl_add_u64 v[4:5], v[2:3], 0, s[42:43]
	s_movk_i32 s42, 0x1000
	s_cselect_b32 s3, 0, 0
	v_mul_lo_u32 v0, v0, s50
	v_add_co_u32_e32 v2, vcc, s42, v2
	s_add_i32 s42, s3, s57
	v_or_b32_e32 v6, v0, v213
	v_or_b32_e32 v0, v0, v228
	v_addc_co_u32_e32 v3, vcc, 0, v3, vcc
	global_load_dwordx4 v[162:165], v[4:5], off offset:32
	global_load_dwordx4 v[166:169], v[4:5], off offset:64
	global_load_dwordx4 v[170:173], v[4:5], off offset:96
	global_load_dwordx4 v[174:177], v[4:5], off offset:128
	global_load_dwordx4 v[178:181], v[4:5], off offset:160
	global_load_dwordx4 v[182:185], v[4:5], off offset:192
	global_load_dwordx4 v[186:189], v[2:3], off offset:2048
	global_load_dwordx4 v[190:193], v[4:5], off offset:224
	s_add_i32 m0, s42, 0x10000
	v_add_u32_e32 v0, 0xc000, v0
	global_load_lds_dwordx4 v6, s[40:41]
	s_add_i32 m0, s42, 0x10400
	s_add_i32 s3, s58, s3
	global_load_lds_dwordx4 v0, s[40:41]
	v_lshlrev_b32_e32 v0, 1, v8
	v_lshl_add_u64 v[2:3], s[8:9], 0, v[0:1]
	s_mov_b32 m0, s3
	s_mov_b64 s[40:41], 0x80
	global_load_lds_dwordx4 v0, s[8:9]
	v_lshl_add_u64 v[4:5], v[2:3], 0, s[40:41]
	s_add_i32 m0, s3, 0x400
	v_add3_u32 v0, v215, v7, s62
	global_load_lds_dwordx4 v[4:5], off
	v_lshl_add_u64 v[4:5], v[2:3], 0, s[10:11]
	s_add_i32 m0, s3, 0x800
	v_lshl_add_u64 v[2:3], v[2:3], 0, s[12:13]
	global_load_lds_dwordx4 v[4:5], off
	s_add_i32 m0, s3, 0xc00
	v_mul_lo_u32 v0, v0, s52
	global_load_lds_dwordx4 v[2:3], off
	v_or_b32_e32 v0, v216, v0
	v_readlane_b32 s40, v251, 40
	v_lshlrev_b32_e32 v0, 1, v0
	v_readlane_b32 s41, v251, 41
	s_mul_i32 s60, s60, 0x18000
	v_mov_b32_e32 v14, v1
	v_lshl_add_u64 v[196:197], s[40:41], 0, v[0:1]
	v_add3_u32 v0, v226, s60, v228
	v_lshl_add_u64 v[198:199], s[38:39], 0, v[0:1]
	v_add_u32_e32 v0, s60, v227
	v_mov_b32_e32 v15, v1
	s_waitcnt vmcnt(0)
	v_lshl_add_u64 v[200:201], s[38:39], 0, v[0:1]
	v_mov_b32_e32 v0, v1
	v_mov_b32_e32 v2, v1
	v_mov_b32_e32 v3, v1
	v_mov_b32_e32 v4, v1
	v_mov_b32_e32 v5, v1
	v_mov_b32_e32 v6, v1
	v_mov_b32_e32 v7, v1
	v_mov_b32_e32 v8, v1
	v_mov_b32_e32 v9, v1
	v_mov_b32_e32 v10, v1
	v_mov_b32_e32 v11, v1
	v_mov_b32_e32 v12, v1
	v_mov_b32_e32 v13, v1
	s_waitcnt vmcnt(0)
	v_mov_b64_e32 v[128:129], v[14:15]
	v_mov_b64_e32 v[112:113], v[14:15]
	v_mov_b64_e32 v[96:97], v[14:15]
	v_mov_b64_e32 v[80:81], v[14:15]
	v_mov_b64_e32 v[64:65], v[14:15]
	v_mov_b64_e32 v[48:49], v[14:15]
	v_mov_b64_e32 v[32:33], v[14:15]
	v_readlane_b32 s65, v251, 33
	v_mov_b64_e32 v[126:127], v[12:13]
	v_mov_b64_e32 v[124:125], v[10:11]
	v_mov_b64_e32 v[122:123], v[8:9]
	v_mov_b64_e32 v[120:121], v[6:7]
	v_mov_b64_e32 v[118:119], v[4:5]
	v_mov_b64_e32 v[116:117], v[2:3]
	v_mov_b64_e32 v[114:115], v[0:1]
	v_mov_b64_e32 v[110:111], v[12:13]
	v_mov_b64_e32 v[108:109], v[10:11]
	v_mov_b64_e32 v[106:107], v[8:9]
	v_mov_b64_e32 v[104:105], v[6:7]
	v_mov_b64_e32 v[102:103], v[4:5]
	v_mov_b64_e32 v[100:101], v[2:3]
	v_mov_b64_e32 v[98:99], v[0:1]
	v_mov_b64_e32 v[94:95], v[12:13]
	v_mov_b64_e32 v[92:93], v[10:11]
	v_mov_b64_e32 v[90:91], v[8:9]
	v_mov_b64_e32 v[88:89], v[6:7]
	v_mov_b64_e32 v[86:87], v[4:5]
	v_mov_b64_e32 v[84:85], v[2:3]
	v_mov_b64_e32 v[82:83], v[0:1]
	v_mov_b64_e32 v[78:79], v[12:13]
	v_mov_b64_e32 v[76:77], v[10:11]
	v_mov_b64_e32 v[74:75], v[8:9]
	v_mov_b64_e32 v[72:73], v[6:7]
	v_mov_b64_e32 v[70:71], v[4:5]
	v_mov_b64_e32 v[68:69], v[2:3]
	v_mov_b64_e32 v[66:67], v[0:1]
	v_mov_b64_e32 v[62:63], v[12:13]
	v_mov_b64_e32 v[60:61], v[10:11]
	v_mov_b64_e32 v[58:59], v[8:9]
	v_mov_b64_e32 v[56:57], v[6:7]
	v_mov_b64_e32 v[54:55], v[4:5]
	v_mov_b64_e32 v[52:53], v[2:3]
	v_mov_b64_e32 v[50:51], v[0:1]
	v_mov_b64_e32 v[46:47], v[12:13]
	v_mov_b64_e32 v[44:45], v[10:11]
	v_mov_b64_e32 v[42:43], v[8:9]
	v_mov_b64_e32 v[40:41], v[6:7]
	v_mov_b64_e32 v[38:39], v[4:5]
	v_mov_b64_e32 v[36:37], v[2:3]
	v_mov_b64_e32 v[34:35], v[0:1]
	v_mov_b64_e32 v[30:31], v[12:13]
	v_mov_b64_e32 v[28:29], v[10:11]
	v_mov_b64_e32 v[26:27], v[8:9]
	v_mov_b64_e32 v[24:25], v[6:7]
	v_mov_b64_e32 v[22:23], v[4:5]
	v_mov_b64_e32 v[20:21], v[2:3]
	v_mov_b64_e32 v[18:19], v[0:1]
	v_mov_b64_e32 v[16:17], v[14:15]
	s_mov_b32 s3, s65
	v_add_u32_e32 v233, s4, v211
	v_lshl_add_u32 v232, v209, 2, s61
	v_lshl_add_u32 v231, v210, 2, s61
	v_mov_b32_e32 v237, 0xf149f2ca
	s_movk_i32 s60, 0x7f
	s_mov_b64 s[38:39], s[6:7]
	s_mov_b32 s61, 2
	v_mov_b64_e32 v[14:15], v[12:13]
	v_mov_b64_e32 v[12:13], v[10:11]
	v_mov_b64_e32 v[10:11], v[8:9]
	v_mov_b64_e32 v[8:9], v[6:7]
	v_mov_b64_e32 v[6:7], v[4:5]
	v_mov_b64_e32 v[4:5], v[2:3]
	v_mov_b64_e32 v[2:3], v[0:1]
	v_mov_b32_e32 v0, 0
	s_waitcnt lgkmcnt(0)
	s_barrier
	s_branch .LBB0_2408
